# v29: v17 + setup fixes (transpose loads batched: 16 loads in flight instead of load/wait per element; S5 bbar table loads batched)
# speedup vs baseline: 1.0195x; 1.0195x over previous
; DI void phase_setup(const Params& p, char* lds) {
;     ...
;       const float step = expf(p.s5_log_step[g]);
; #pragma unroll
;       for (int q = 0; q < 4; ++q) { const int idx = tid + q * 256; Cr[idx] = p.s5_c_re[g * 1024 + idx]; Ci[idx] = p.s5_c_im[g * 1024 + idx]; }
;       if (tid < 64) {
;         const int pp = tid;
;         const float lr = p.s5_lam_re[g * 64 + pp], li = p.s5_lam_im[g * 64 + pp];
;         const float mag = expf(lr * step);
;         float sn, cn; sincosf(li * step, &sn, &cn);
;         const float ar = mag * cn, ai = mag * sn;
;         const float den = lr * lr + li * li, xr = ar - 1.0f;
;         const float nr = (xr * lr + ai * li) / den, ni = (ai * lr - xr * li) / den;
; #pragma unroll
;         for (int c = 0; c < 16; ++c) {
;           const float br = p.s5_b_re[(g * 64 + pp) * 16 + c], bi = p.s5_b_im[(g * 64 + pp) * 16 + c];
;           Bbr[pp * 16 + c] = nr * br - ni * bi; Bbi[pp * 16 + c] = nr * bi + ni * br;
;         }
.LBB0_28:
	s_andn2_saveexec_b64 s[0:1], s[0:1]
	v_mul_f32_e64 v0, |v9|, s84
	v_rndne_f32_e32 v0, v0
	v_cvt_i32_f32_e32 v18, v0
	v_fma_f32 v17, v0, s85, |v9|
	v_fmac_f32_e32 v17, 0xb3a22168, v0
	v_fmac_f32_e32 v17, 0xa7c234c4, v0
	s_or_b64 exec, exec, s[0:1]
	s_waitcnt vmcnt(0)
	v_mul_f32_e32 v2, v21, v14
	v_lshlrev_b32_e32 v86, 4, v8
	v_mul_f32_e32 v3, 0x3fb8aa3b, v2
	v_lshlrev_b64 v[0:1], 2, v[86:87]
	v_fma_f32 v4, v2, s72, -v3
	v_lshl_add_u64 v[10:11], s[28:29], 0, v[0:1]
	v_lshl_add_u64 v[12:13], s[30:31], 0, v[0:1]
	v_rndne_f32_e32 v0, v3
	v_fmac_f32_e32 v4, 0x32a5705f, v2
	v_sub_f32_e32 v1, v3, v0
	v_add_f32_e32 v1, v1, v4
	global_load_dwordx4 v[24:27], v[12:13], off
	global_load_dwordx4 v[28:31], v[10:11], off
	v_exp_f32_e32 v1, v1
	v_cvt_i32_f32_e32 v0, v0
	global_load_dwordx4 v[32:35], v[12:13], off offset:16
	global_load_dwordx4 v[36:39], v[10:11], off offset:16
	v_cmp_ngt_f32_e32 vcc, s73, v2
	v_mul_f32_e32 v48, v17, v17
	v_ldexp_f32 v0, v1, v0
	v_cndmask_b32_e32 v0, 0, v0, vcc
	v_cmp_nlt_f32_e32 vcc, s74, v2
	v_xor_b32_e32 v16, v16, v9
	s_nop 0
	v_cndmask_b32_e32 v23, v203, v0, vcc
	v_fmamk_f32 v0, v48, 0xb94c1982, v201
	v_fmaak_f32 v49, v48, v0, 0xbe2aaa9d
	global_load_dwordx4 v[0:3], v[12:13], off offset:48
	global_load_dwordx4 v[40:43], v[12:13], off offset:32
	global_load_dwordx4 v[4:7], v[10:11], off offset:48
	global_load_dwordx4 v[44:47], v[10:11], off offset:32
	v_mul_f32_e32 v49, v48, v49
	v_fmac_f32_e32 v17, v17, v49
	v_fmamk_f32 v49, v48, 0x37d75334, v202
	v_fmaak_f32 v49, v48, v49, 0x3d2aabf7
	v_fmaak_f32 v49, v48, v49, 0xbf000004
	v_fma_f32 v48, v48, v49, 1.0
	v_lshlrev_b32_e32 v49, 30, v18
	v_and_b32_e32 v18, 1, v18
	v_cmp_eq_u32_e32 vcc, 0, v18
	v_and_b32_e32 v50, 0x80000000, v49
	s_nop 0
	v_cndmask_b32_e32 v18, v48, v17, vcc
	v_xor_b32_e32 v17, 0x80000000, v17
	v_xor_b32_e32 v16, v16, v18
	v_cndmask_b32_e32 v17, v17, v48, vcc
	v_xor_b32_e32 v16, v16, v50
	v_bitop3_b32 v17, v17, v49, s86 bitop3:0x78
	v_cmp_class_f32_e64 vcc, v9, s87
	v_mov_b32_e32 v18, v15
	v_pk_mul_f32 v[48:49], v[14:15], v[14:15]
	v_cndmask_b32_e32 v9, v206, v17, vcc
	v_cndmask_b32_e32 v16, v206, v16, vcc
	v_mul_f32_e32 v17, v23, v16
	v_fma_f32 v16, v23, v9, -1.0
	v_pk_mul_f32 v[50:51], v[18:19], v[16:17] op_sel:[0,1] op_sel_hi:[0,0]
	v_pk_fma_f32 v[52:53], v[14:15], v[16:17], v[50:51] op_sel_hi:[0,1,1] neg_lo:[0,0,1] neg_hi:[0,0,1]
	v_pk_add_f32 v[48:49], v[48:49], v[48:49] op_sel:[0,1] op_sel_hi:[0,1]
	v_div_scale_f32 v18, s[0:1], v49, v49, v53
	v_rcp_f32_e32 v52, v18
	v_pk_fma_f32 v[14:15], v[14:15], v[16:17], v[50:51]
	s_nop 0
	v_fma_f32 v15, -v18, v52, 1.0
	v_fmac_f32_e32 v52, v15, v52
	v_div_scale_f32 v15, vcc, v53, v49, v53
	v_mul_f32_e32 v16, v15, v52
	v_fma_f32 v50, -v18, v16, v15
	v_fmac_f32_e32 v16, v50, v52
	v_div_scale_f32 v50, s[0:1], v48, v48, v14
	v_rcp_f32_e32 v51, v50
	v_fma_f32 v15, -v18, v16, v15
	v_div_fmas_f32 v15, v15, v52, v16
	v_div_fixup_f32 v18, v15, v49, v53
	v_fma_f32 v15, -v50, v51, 1.0
	v_fmac_f32_e32 v51, v15, v51
	v_div_scale_f32 v15, vcc, v14, v48, v14
	v_mul_f32_e32 v16, v15, v51
	v_fma_f32 v49, -v50, v16, v15
	v_fmac_f32_e32 v16, v49, v51
	v_fma_f32 v15, -v50, v16, v15
	v_div_fmas_f32 v15, v15, v51, v16
	v_div_fixup_f32 v14, v15, v48, v14
	v_cmp_eq_u32_e32 vcc, 0, v20
	s_waitcnt vmcnt(7)
	v_pk_mul_f32 v[48:49], v[24:25], v[18:19] op_sel_hi:[1,0]
	v_pk_mul_f32 v[24:25], v[24:25], v[14:15] op_sel_hi:[1,0]
	s_waitcnt vmcnt(6)
	v_pk_fma_f32 v[48:49], v[28:29], v[14:15], v[48:49] op_sel_hi:[1,0,1] neg_lo:[0,0,1] neg_hi:[0,0,1]
	v_pk_fma_f32 v[24:25], v[28:29], v[18:19], v[24:25] op_sel_hi:[1,0,1]
	v_pk_mul_f32 v[28:29], v[26:27], v[18:19] op_sel_hi:[1,0]
	v_pk_mul_f32 v[26:27], v[14:15], v[26:27] op_sel_hi:[0,1]
	v_pk_fma_f32 v[26:27], v[30:31], v[18:19], v[26:27] op_sel_hi:[1,0,1]
	ds_write_b128 v168, v[24:27] offset:12288
	s_waitcnt vmcnt(5)
	v_pk_mul_f32 v[26:27], v[14:15], v[32:33] op_sel_hi:[0,1]
	v_pk_fma_f32 v[50:51], v[30:31], v[14:15], v[28:29] op_sel_hi:[1,0,1] neg_lo:[0,0,1] neg_hi:[0,0,1]
	v_pk_mul_f32 v[24:25], v[18:19], v[32:33] op_sel_hi:[0,1]
	s_waitcnt vmcnt(4)
	v_pk_fma_f32 v[28:29], v[18:19], v[36:37], v[26:27] op_sel_hi:[0,1,1]
	v_pk_mul_f32 v[26:27], v[18:19], v[34:35] op_sel_hi:[0,1]
	v_pk_fma_f32 v[24:25], v[14:15], v[36:37], v[24:25] op_sel_hi:[0,1,1] neg_lo:[0,0,1] neg_hi:[0,0,1]
	v_pk_fma_f32 v[26:27], v[14:15], v[38:39], v[26:27] op_sel_hi:[0,1,1] neg_lo:[0,0,1] neg_hi:[0,0,1]
	ds_write_b128 v168, v[24:27] offset:8208
	v_pk_mul_f32 v[24:25], v[14:15], v[34:35] op_sel_hi:[0,1]
	v_pk_fma_f32 v[30:31], v[18:19], v[38:39], v[24:25] op_sel_hi:[0,1,1]
	s_waitcnt vmcnt(2)
	v_pk_mul_f32 v[26:27], v[14:15], v[40:41] op_sel_hi:[0,1]
	ds_write_b128 v168, v[28:31] offset:12304
	v_pk_mul_f32 v[24:25], v[18:19], v[40:41] op_sel_hi:[0,1]
	s_waitcnt vmcnt(0)
	v_pk_fma_f32 v[28:29], v[18:19], v[44:45], v[26:27] op_sel_hi:[0,1,1]
	v_pk_mul_f32 v[26:27], v[18:19], v[42:43] op_sel_hi:[0,1]
	v_pk_fma_f32 v[24:25], v[14:15], v[44:45], v[24:25] op_sel_hi:[0,1,1] neg_lo:[0,0,1] neg_hi:[0,0,1]
	v_pk_fma_f32 v[26:27], v[14:15], v[46:47], v[26:27] op_sel_hi:[0,1,1] neg_lo:[0,0,1] neg_hi:[0,0,1]
	ds_write_b128 v168, v[24:27] offset:8224
	v_pk_mul_f32 v[24:25], v[14:15], v[42:43] op_sel_hi:[0,1]
	v_pk_fma_f32 v[30:31], v[18:19], v[46:47], v[24:25] op_sel_hi:[0,1,1]
	v_pk_mul_f32 v[24:25], v[18:19], v[0:1] op_sel_hi:[0,1]
	v_pk_mul_f32 v[0:1], v[14:15], v[0:1] op_sel_hi:[0,1]
	v_pk_fma_f32 v[24:25], v[14:15], v[4:5], v[24:25] op_sel_hi:[0,1,1] neg_lo:[0,0,1] neg_hi:[0,0,1]
	v_pk_fma_f32 v[0:1], v[18:19], v[4:5], v[0:1] op_sel_hi:[0,1,1]
	v_pk_mul_f32 v[4:5], v[18:19], v[2:3] op_sel_hi:[0,1]
	v_pk_mul_f32 v[2:3], v[14:15], v[2:3] op_sel_hi:[0,1]
	v_pk_fma_f32 v[26:27], v[14:15], v[6:7], v[4:5] op_sel_hi:[0,1,1] neg_lo:[0,0,1] neg_hi:[0,0,1]
	v_pk_fma_f32 v[2:3], v[18:19], v[6:7], v[2:3] op_sel_hi:[0,1,1]
	ds_write_b128 v168, v[48:51] offset:8192
	ds_write_b128 v168, v[28:31] offset:12320
	ds_write_b128 v168, v[24:27] offset:8240
	ds_write_b128 v168, v[0:3] offset:12336
	s_and_b64 exec, exec, vcc
	s_cbranch_execz .LBB0_32
; DI void phase_setup(const Params& p, char* lds) {
;     ...
;         if (d0 == 0) {
;           float* abar = (float*)(p.ws + W_ABAR);
;           abar[(g * 64 + pp) * 2] = ar; abar[(g * 64 + pp) * 2 + 1] = ai;
;           float* bb = (float*)(p.ws + W_BBAR);
; #pragma unroll
;           for (int c = 0; c < 16; ++c) {
;             const float br = p.s5_b_re[(g * 64 + pp) * 16 + c], bi = p.s5_b_im[(g * 64 + pp) * 16 + c];
;             bb[((g * 64 + pp) * 16 + c) * 2] = nr * br - ni * bi;
;             bb[((g * 64 + pp) * 16 + c) * 2 + 1] = nr * bi + ni * br;
;           }
	v_lshlrev_b32_e32 v3, 1, v86
	v_lshlrev_b32_e32 v86, 1, v8
	v_mul_f32_e32 v16, v23, v9
	v_lshl_add_u64 v[0:1], v[86:87], 2, s[16:17]
	global_store_dwordx2 v[0:1], v[16:17], off
	global_load_dword v218, v[12:13], off
	global_load_dword v234, v[10:11], off
	global_load_dword v219, v[12:13], off offset:4
	global_load_dword v235, v[10:11], off offset:4
	global_load_dword v220, v[12:13], off offset:8
	global_load_dword v236, v[10:11], off offset:8
	global_load_dword v221, v[12:13], off offset:12
	global_load_dword v237, v[10:11], off offset:12
	global_load_dword v222, v[12:13], off offset:16
	global_load_dword v238, v[10:11], off offset:16
	global_load_dword v223, v[12:13], off offset:20
	global_load_dword v239, v[10:11], off offset:20
	global_load_dword v224, v[12:13], off offset:24
	global_load_dword v240, v[10:11], off offset:24
	global_load_dword v225, v[12:13], off offset:28
	global_load_dword v241, v[10:11], off offset:28
	global_load_dword v226, v[12:13], off offset:32
	global_load_dword v242, v[10:11], off offset:32
	global_load_dword v227, v[12:13], off offset:36
	global_load_dword v243, v[10:11], off offset:36
	global_load_dword v228, v[12:13], off offset:40
	global_load_dword v244, v[10:11], off offset:40
	global_load_dword v229, v[12:13], off offset:44
	global_load_dword v245, v[10:11], off offset:44
	global_load_dword v230, v[12:13], off offset:48
	global_load_dword v246, v[10:11], off offset:48
	global_load_dword v231, v[12:13], off offset:52
	global_load_dword v247, v[10:11], off offset:52
	global_load_dword v232, v[12:13], off offset:56
	global_load_dword v248, v[10:11], off offset:56
	global_load_dword v233, v[12:13], off offset:60
	global_load_dword v249, v[10:11], off offset:60
	s_waitcnt vmcnt(0)
; DI void phase_setup(const Params& p, char* lds) {
;     ...
;           for (int c = 0; c < 16; ++c) {
;             const float br = p.s5_b_re[(g * 64 + pp) * 16 + c], bi = p.s5_b_im[(g * 64 + pp) * 16 + c];
;             bb[((g * 64 + pp) * 16 + c) * 2] = nr * br - ni * bi;
;             bb[((g * 64 + pp) * 16 + c) * 2 + 1] = nr * bi + ni * br;
;           }
	v_mov_b32_e32 v0, v218
	s_nop 0
	v_mov_b32_e32 v2, v234
	v_mov_b32_e32 v15, v18
	v_lshlrev_b32_e32 v86, 5, v8
	v_lshl_add_u64 v[4:5], v[86:87], 2, s[52:53]
	v_or_b32_e32 v86, 2, v3
	v_pk_mul_f32 v[0:1], v[14:15], v[0:1] op_sel:[1,0] op_sel_hi:[0,0]
	v_pk_fma_f32 v[6:7], v[14:15], v[2:3], v[0:1] neg_lo:[0,0,1] neg_hi:[0,0,1]
	v_pk_fma_f32 v[0:1], v[14:15], v[2:3], v[0:1] op_sel_hi:[1,0,1]
	s_nop 0
	v_mov_b32_e32 v7, v1
	global_store_dwordx2 v[4:5], v[6:7], off
	v_mov_b32_e32 v0, v219
	v_mov_b32_e32 v2, v235
	v_lshl_add_u64 v[4:5], v[86:87], 2, s[52:53]
	v_or_b32_e32 v86, 4, v3
	v_pk_mul_f32 v[0:1], v[14:15], v[0:1] op_sel:[1,0] op_sel_hi:[0,0]
	v_pk_fma_f32 v[6:7], v[14:15], v[2:3], v[0:1] neg_lo:[0,0,1] neg_hi:[0,0,1]
	v_pk_fma_f32 v[0:1], v[14:15], v[2:3], v[0:1] op_sel_hi:[1,0,1]
	s_nop 0
	v_mov_b32_e32 v7, v1
	global_store_dwordx2 v[4:5], v[6:7], off
	v_mov_b32_e32 v0, v220
	v_mov_b32_e32 v2, v236
	v_lshl_add_u64 v[4:5], v[86:87], 2, s[52:53]
	v_or_b32_e32 v86, 6, v3
	v_pk_mul_f32 v[0:1], v[14:15], v[0:1] op_sel:[1,0] op_sel_hi:[0,0]
	v_pk_fma_f32 v[6:7], v[14:15], v[2:3], v[0:1] neg_lo:[0,0,1] neg_hi:[0,0,1]
	v_pk_fma_f32 v[0:1], v[14:15], v[2:3], v[0:1] op_sel_hi:[1,0,1]
	s_nop 0
	v_mov_b32_e32 v7, v1
	global_store_dwordx2 v[4:5], v[6:7], off
	v_mov_b32_e32 v0, v221
	v_mov_b32_e32 v2, v237
	v_lshl_add_u64 v[4:5], v[86:87], 2, s[52:53]
	v_or_b32_e32 v86, 8, v3
	v_pk_mul_f32 v[0:1], v[14:15], v[0:1] op_sel:[1,0] op_sel_hi:[0,0]
	v_pk_fma_f32 v[6:7], v[14:15], v[2:3], v[0:1] neg_lo:[0,0,1] neg_hi:[0,0,1]
	v_pk_fma_f32 v[0:1], v[14:15], v[2:3], v[0:1] op_sel_hi:[1,0,1]
	s_nop 0
	v_mov_b32_e32 v7, v1
	global_store_dwordx2 v[4:5], v[6:7], off
	v_mov_b32_e32 v0, v222
	v_mov_b32_e32 v2, v238
	v_lshl_add_u64 v[4:5], v[86:87], 2, s[52:53]
	v_or_b32_e32 v86, 10, v3
	v_pk_mul_f32 v[0:1], v[14:15], v[0:1] op_sel:[1,0] op_sel_hi:[0,0]
	v_pk_fma_f32 v[6:7], v[14:15], v[2:3], v[0:1] neg_lo:[0,0,1] neg_hi:[0,0,1]
	v_pk_fma_f32 v[0:1], v[14:15], v[2:3], v[0:1] op_sel_hi:[1,0,1]
	s_nop 0
	v_mov_b32_e32 v7, v1
	global_store_dwordx2 v[4:5], v[6:7], off
	v_mov_b32_e32 v0, v223
	v_mov_b32_e32 v2, v239
	v_lshl_add_u64 v[4:5], v[86:87], 2, s[52:53]
	v_or_b32_e32 v86, 12, v3
	v_pk_mul_f32 v[0:1], v[14:15], v[0:1] op_sel:[1,0] op_sel_hi:[0,0]
	v_pk_fma_f32 v[6:7], v[14:15], v[2:3], v[0:1] neg_lo:[0,0,1] neg_hi:[0,0,1]
	v_pk_fma_f32 v[0:1], v[14:15], v[2:3], v[0:1] op_sel_hi:[1,0,1]
	s_nop 0
	v_mov_b32_e32 v7, v1
	global_store_dwordx2 v[4:5], v[6:7], off
	v_mov_b32_e32 v0, v224
	v_mov_b32_e32 v2, v240
	v_lshl_add_u64 v[4:5], v[86:87], 2, s[52:53]
	v_or_b32_e32 v86, 14, v3
	v_pk_mul_f32 v[0:1], v[14:15], v[0:1] op_sel:[1,0] op_sel_hi:[0,0]
	v_pk_fma_f32 v[6:7], v[14:15], v[2:3], v[0:1] neg_lo:[0,0,1] neg_hi:[0,0,1]
	v_pk_fma_f32 v[0:1], v[14:15], v[2:3], v[0:1] op_sel_hi:[1,0,1]
	s_nop 0
	v_mov_b32_e32 v7, v1
	global_store_dwordx2 v[4:5], v[6:7], off
	v_mov_b32_e32 v0, v225
	v_mov_b32_e32 v2, v241
	v_lshl_add_u64 v[4:5], v[86:87], 2, s[52:53]
	v_or_b32_e32 v86, 16, v3
	v_pk_mul_f32 v[0:1], v[14:15], v[0:1] op_sel:[1,0] op_sel_hi:[0,0]
	v_pk_fma_f32 v[6:7], v[14:15], v[2:3], v[0:1] neg_lo:[0,0,1] neg_hi:[0,0,1]
	v_pk_fma_f32 v[0:1], v[14:15], v[2:3], v[0:1] op_sel_hi:[1,0,1]
	s_nop 0
	v_mov_b32_e32 v7, v1
	global_store_dwordx2 v[4:5], v[6:7], off
	v_mov_b32_e32 v0, v226
	v_mov_b32_e32 v2, v242
	v_lshl_add_u64 v[4:5], v[86:87], 2, s[52:53]
	v_or_b32_e32 v86, 18, v3
	v_pk_mul_f32 v[0:1], v[14:15], v[0:1] op_sel:[1,0] op_sel_hi:[0,0]
	v_pk_fma_f32 v[6:7], v[14:15], v[2:3], v[0:1] neg_lo:[0,0,1] neg_hi:[0,0,1]
	v_pk_fma_f32 v[0:1], v[14:15], v[2:3], v[0:1] op_sel_hi:[1,0,1]
	s_nop 0
	v_mov_b32_e32 v7, v1
	global_store_dwordx2 v[4:5], v[6:7], off
	v_mov_b32_e32 v0, v227
	v_mov_b32_e32 v2, v243
	v_lshl_add_u64 v[4:5], v[86:87], 2, s[52:53]
	v_or_b32_e32 v86, 20, v3
	v_pk_mul_f32 v[0:1], v[14:15], v[0:1] op_sel:[1,0] op_sel_hi:[0,0]
	v_pk_fma_f32 v[6:7], v[14:15], v[2:3], v[0:1] neg_lo:[0,0,1] neg_hi:[0,0,1]
	v_pk_fma_f32 v[0:1], v[14:15], v[2:3], v[0:1] op_sel_hi:[1,0,1]
	s_nop 0
	v_mov_b32_e32 v7, v1
	global_store_dwordx2 v[4:5], v[6:7], off
	v_mov_b32_e32 v0, v228
	v_mov_b32_e32 v2, v244
	v_lshl_add_u64 v[4:5], v[86:87], 2, s[52:53]
	v_or_b32_e32 v86, 22, v3
	v_pk_mul_f32 v[0:1], v[14:15], v[0:1] op_sel:[1,0] op_sel_hi:[0,0]
	v_pk_fma_f32 v[6:7], v[14:15], v[2:3], v[0:1] neg_lo:[0,0,1] neg_hi:[0,0,1]
	v_pk_fma_f32 v[0:1], v[14:15], v[2:3], v[0:1] op_sel_hi:[1,0,1]
	s_nop 0
	v_mov_b32_e32 v7, v1
	global_store_dwordx2 v[4:5], v[6:7], off
	v_mov_b32_e32 v0, v229
	v_mov_b32_e32 v2, v245
	v_lshl_add_u64 v[4:5], v[86:87], 2, s[52:53]
	v_or_b32_e32 v86, 24, v3
	v_pk_mul_f32 v[0:1], v[14:15], v[0:1] op_sel:[1,0] op_sel_hi:[0,0]
	v_pk_fma_f32 v[6:7], v[14:15], v[2:3], v[0:1] neg_lo:[0,0,1] neg_hi:[0,0,1]
	v_pk_fma_f32 v[0:1], v[14:15], v[2:3], v[0:1] op_sel_hi:[1,0,1]
	s_nop 0
	v_mov_b32_e32 v7, v1
	global_store_dwordx2 v[4:5], v[6:7], off
	v_mov_b32_e32 v0, v230
	v_mov_b32_e32 v2, v246
	v_lshl_add_u64 v[4:5], v[86:87], 2, s[52:53]
	v_or_b32_e32 v86, 26, v3
	v_pk_mul_f32 v[0:1], v[14:15], v[0:1] op_sel:[1,0] op_sel_hi:[0,0]
	v_pk_fma_f32 v[6:7], v[14:15], v[2:3], v[0:1] neg_lo:[0,0,1] neg_hi:[0,0,1]
	v_pk_fma_f32 v[0:1], v[14:15], v[2:3], v[0:1] op_sel_hi:[1,0,1]
	s_nop 0
	v_mov_b32_e32 v7, v1
	global_store_dwordx2 v[4:5], v[6:7], off
	v_mov_b32_e32 v0, v231
	v_mov_b32_e32 v2, v247
	v_lshl_add_u64 v[4:5], v[86:87], 2, s[52:53]
	v_or_b32_e32 v86, 28, v3
	v_pk_mul_f32 v[0:1], v[14:15], v[0:1] op_sel:[1,0] op_sel_hi:[0,0]
	v_pk_fma_f32 v[6:7], v[14:15], v[2:3], v[0:1] neg_lo:[0,0,1] neg_hi:[0,0,1]
	v_pk_fma_f32 v[0:1], v[14:15], v[2:3], v[0:1] op_sel_hi:[1,0,1]
	s_nop 0
	v_mov_b32_e32 v7, v1
	global_store_dwordx2 v[4:5], v[6:7], off
	v_mov_b32_e32 v0, v232
	v_mov_b32_e32 v2, v248
	v_lshl_add_u64 v[4:5], v[86:87], 2, s[52:53]
	v_or_b32_e32 v86, 30, v3
	v_pk_mul_f32 v[0:1], v[14:15], v[0:1] op_sel:[1,0] op_sel_hi:[0,0]
	v_pk_fma_f32 v[6:7], v[14:15], v[2:3], v[0:1] neg_lo:[0,0,1] neg_hi:[0,0,1]
	v_pk_fma_f32 v[0:1], v[14:15], v[2:3], v[0:1] op_sel_hi:[1,0,1]
	s_nop 0
	v_mov_b32_e32 v7, v1
	global_store_dwordx2 v[4:5], v[6:7], off
	v_mov_b32_e32 v0, v233
	v_mov_b32_e32 v2, v249
	v_lshl_add_u64 v[4:5], v[86:87], 2, s[52:53]
	v_pk_mul_f32 v[0:1], v[14:15], v[0:1] op_sel:[1,0] op_sel_hi:[0,0]
	v_pk_fma_f32 v[6:7], v[14:15], v[2:3], v[0:1] neg_lo:[0,0,1] neg_hi:[0,0,1]
	v_pk_fma_f32 v[0:1], v[14:15], v[2:3], v[0:1] op_sel_hi:[1,0,1]
	s_nop 0
	v_mov_b32_e32 v7, v1
	global_store_dwordx2 v[4:5], v[6:7], off

; DI void phase_setup(const Params& p, char* lds) {
;     ...
;       const int tk = t / ntn, tn = t % ntn, k0 = tk * 64, n0 = tn * 64;
;       float* tl = (float*)lds;
;       const int tx = tid & 63, ty = tid >> 6;
; #pragma unroll 4
;       for (int i = 0; i < 16; ++i) {
;         const int k = k0 + ty * 16 + i, n = n0 + tx;
;         tl[(ty * 16 + i) * 65 + tx] = (n < N) ? W[(size_t)k * N + n] : 0.f;
;       }
.LBB0_58:
	s_or_b64 exec, exec, s[2:3]
	v_cvt_f32_u32_sdwa v7, v6 dst_sel:DWORD dst_unused:UNUSED_PAD src0_sel:WORD_0
	v_add_u32_e32 v8, v18, v3
	v_cvt_f32_u32_sdwa v9, v8 dst_sel:DWORD dst_unused:UNUSED_PAD src0_sel:WORD_0
	v_mov_b32_e32 v3, v87
	v_rcp_iflag_f32_e32 v10, v7
	s_mov_b32 s10, 0
	v_mul_f32_e32 v10, v9, v10
	v_trunc_f32_e32 v10, v10
	v_cvt_u32_f32_e32 v11, v10
	v_fma_f32 v9, -v10, v7, v9
	v_cmp_ge_f32_e64 vcc, |v9|, v7
	s_nop 1
	v_addc_co_u32_e32 v7, vcc, 0, v11, vcc
	v_mul_lo_u16_e32 v6, v7, v6
	v_sub_u16_e32 v6, v8, v6
	v_lshlrev_b32_sdwa v13, v213, v7 dst_sel:DWORD dst_unused:UNUSED_PAD src0_sel:DWORD src1_sel:WORD_0
	v_lshlrev_b16_e32 v12, 6, v6
	v_or_b32_e32 v6, v133, v12
	v_or_b32_e32 v14, v141, v13
	v_cmp_lt_u32_e32 vcc, v6, v2
	v_lshlrev_b32_e32 v86, 2, v6
	v_add_u32_e32 v6, 3, v14
	v_add_u32_e32 v8, 2, v14
	v_lshl_add_u64 v[4:5], v[4:5], 0, v[86:87]
	v_mul_hi_u32_u24_e32 v7, v6, v2
	v_mul_u32_u24_e32 v6, v6, v2
	v_lshlrev_b32_e32 v86, 4, v2
	v_mul_hi_u32_u24_e32 v9, v8, v2
	v_mul_u32_u24_e32 v8, v8, v2
	v_mad_u64_u32 v[10:11], s[2:3], v2, v14, v[2:3]
	v_mul_hi_u32_u24_e32 v3, v2, v14
	v_mul_u32_u24_e32 v2, v2, v14
	v_lshlrev_b64 v[6:7], 2, v[6:7]
	v_lshlrev_b64 v[8:9], 2, v[8:9]
	v_lshlrev_b64 v[10:11], 2, v[10:11]
	v_lshlrev_b64 v[2:3], 2, v[2:3]
	v_mov_b32_e32 v220, 0
	v_mov_b32_e32 v221, 0
	v_mov_b32_e32 v222, 0
	v_mov_b32_e32 v223, 0
	v_mov_b32_e32 v224, 0
	v_mov_b32_e32 v225, 0
	v_mov_b32_e32 v226, 0
	v_mov_b32_e32 v227, 0
	v_mov_b32_e32 v228, 0
	v_mov_b32_e32 v229, 0
	v_mov_b32_e32 v230, 0
	v_mov_b32_e32 v231, 0
	v_mov_b32_e32 v232, 0
	v_mov_b32_e32 v233, 0
	v_mov_b32_e32 v234, 0
	v_mov_b32_e32 v235, 0
	s_and_saveexec_b64 s[2:3], vcc
	s_cbranch_execz .Ltr_skip
	v_lshl_add_u64 v[16:17], v[4:5], 0, v[2:3]
	global_load_dword v220, v[16:17], off
	v_lshl_add_u64 v[16:17], v[4:5], 0, v[10:11]
	global_load_dword v221, v[16:17], off
	v_lshl_add_u64 v[16:17], v[4:5], 0, v[8:9]
	global_load_dword v222, v[16:17], off
	v_lshl_add_u64 v[16:17], v[4:5], 0, v[6:7]
	global_load_dword v223, v[16:17], off
	v_lshl_add_u64 v[4:5], v[4:5], 0, v[86:87]
	v_lshl_add_u64 v[16:17], v[4:5], 0, v[2:3]
	global_load_dword v224, v[16:17], off
	v_lshl_add_u64 v[16:17], v[4:5], 0, v[10:11]
	global_load_dword v225, v[16:17], off
	v_lshl_add_u64 v[16:17], v[4:5], 0, v[8:9]
	global_load_dword v226, v[16:17], off
	v_lshl_add_u64 v[16:17], v[4:5], 0, v[6:7]
	global_load_dword v227, v[16:17], off
	v_lshl_add_u64 v[4:5], v[4:5], 0, v[86:87]
	v_lshl_add_u64 v[16:17], v[4:5], 0, v[2:3]
	global_load_dword v228, v[16:17], off
	v_lshl_add_u64 v[16:17], v[4:5], 0, v[10:11]
	global_load_dword v229, v[16:17], off
	v_lshl_add_u64 v[16:17], v[4:5], 0, v[8:9]
	global_load_dword v230, v[16:17], off
	v_lshl_add_u64 v[16:17], v[4:5], 0, v[6:7]
	global_load_dword v231, v[16:17], off
	v_lshl_add_u64 v[4:5], v[4:5], 0, v[86:87]
	v_lshl_add_u64 v[16:17], v[4:5], 0, v[2:3]
	global_load_dword v232, v[16:17], off
	v_lshl_add_u64 v[16:17], v[4:5], 0, v[10:11]
	global_load_dword v233, v[16:17], off
	v_lshl_add_u64 v[16:17], v[4:5], 0, v[8:9]
	global_load_dword v234, v[16:17], off
	v_lshl_add_u64 v[16:17], v[4:5], 0, v[6:7]
	global_load_dword v235, v[16:17], off
	v_lshl_add_u64 v[4:5], v[4:5], 0, v[86:87]
.Ltr_skip:
	s_or_b64 exec, exec, s[2:3]
	s_waitcnt vmcnt(0)
	ds_write_b32 v196, v220
	ds_write_b32 v196, v221 offset:260
	ds_write_b32 v196, v222 offset:520
	ds_write_b32 v196, v223 offset:780
	ds_write_b32 v196, v224 offset:1040
	ds_write_b32 v196, v225 offset:1300
	ds_write_b32 v196, v226 offset:1560
	ds_write_b32 v196, v227 offset:1820
	ds_write_b32 v196, v228 offset:2080
	ds_write_b32 v196, v229 offset:2340
	ds_write_b32 v196, v230 offset:2600
	ds_write_b32 v196, v231 offset:2860
	ds_write_b32 v196, v232 offset:3120
	ds_write_b32 v196, v233 offset:3380
	ds_write_b32 v196, v234 offset:3640
	ds_write_b32 v196, v235 offset:3900
